# P1/P8: write-through stores in a workgroup's last unit of the phase only (drain under the epilogue math), stacked on v58
# speedup vs baseline: 1.0007x; 1.0001x over previous
.LBB0_204:
	v_cndmask_b32_e64 v140, 0, 1, s[4:5]
	s_and_b32 s2, s53, 1
	v_mov_b32_e32 v150, v143
	v_mov_b32_e32 v141, v1
	v_cmp_ne_u32_e64 s[6:7], 1, v140
	s_cmp_lg_u64 s[4:5], 0
	s_cselect_b32 s98, 1, 0
	s_andn2_b64 vcc, exec, s[4:5]
	s_mov_b64 s[4:5], -1
	s_cbranch_vccnz .LBB0_206
	s_lshl_b32 s3, s2, 12
	s_mov_b64 s[4:5], 0

.LBB0_208:
	s_add_u32 s4, s46, 0xfffffe00
	s_addc_u32 s5, s47, -1
	s_add_i32 s2, s76, s3
	v_lshl_add_u32 v140, v141, 4, s2
	ds_read_b128 v[152:155], v140
	ds_read_b128 v[156:159], v140 offset:256
	ds_read_b128 v[160:163], v140 offset:512
	ds_read_b128 v[164:167], v140 offset:768
	s_waitcnt lgkmcnt(0)
	s_waitcnt lgkmcnt(0)
	v_mov_b32_e32 v168, v153
	v_mov_b32_e32 v169, v154
	v_mov_b32_e32 v153, v155
	v_pk_add_f32 v[152:153], v[168:169], v[152:153]
	s_lshl_b32 s2, s10, 8
	v_add_f32_e32 v149, v152, v153
	v_mov_b32_e32 v152, v157
	v_mov_b32_e32 v153, v158
	v_mov_b32_e32 v157, v159
	v_fmamk_f32 v149, v149, 0x3a800000, v148
	v_pk_add_f32 v[152:153], v[152:153], v[156:157]
	v_rsq_f32_e32 v170, v149
	v_add_f32_e32 v149, v152, v153
	v_mov_b32_e32 v152, v161
	v_mov_b32_e32 v153, v162
	v_mov_b32_e32 v161, v163
	v_fmamk_f32 v149, v149, 0x3a800000, v148
	v_pk_add_f32 v[152:153], v[152:153], v[160:161]
	v_rsq_f32_e32 v171, v149
	v_add_f32_e32 v149, v152, v153
	v_mov_b32_e32 v152, v165
	v_mov_b32_e32 v153, v166
	v_mov_b32_e32 v165, v167
	v_fmamk_f32 v149, v149, 0x3a800000, v148
	v_pk_add_f32 v[152:153], v[152:153], v[164:165]
	v_rsq_f32_e32 v172, v149
	v_add_f32_e32 v149, v152, v153
	ds_read_b128 v[152:155], v140 offset:2048
	ds_read_b128 v[156:159], v140 offset:2304
	ds_read_b128 v[160:163], v140 offset:2560
	ds_read_b128 v[164:167], v140 offset:2816
	v_fmamk_f32 v149, v149, 0x3a800000, v148
	s_waitcnt lgkmcnt(0)
	v_mov_b32_e32 v168, v153
	v_mov_b32_e32 v169, v154
	v_mov_b32_e32 v153, v155
	v_pk_add_f32 v[152:153], v[168:169], v[152:153]
	v_rsq_f32_e32 v173, v149
	v_add_f32_e32 v140, v152, v153
	v_mov_b32_e32 v152, v157
	v_mov_b32_e32 v153, v158
	v_mov_b32_e32 v157, v159
	v_fmamk_f32 v140, v140, 0x3a800000, v148
	v_pk_add_f32 v[152:153], v[152:153], v[156:157]
	v_rsq_f32_e32 v168, v140
	v_add_f32_e32 v140, v152, v153
	v_mov_b32_e32 v152, v161
	v_mov_b32_e32 v153, v162
	v_mov_b32_e32 v161, v163
	v_fmamk_f32 v140, v140, 0x3a800000, v148
	v_pk_add_f32 v[152:153], v[152:153], v[160:161]
	v_rsq_f32_e32 v169, v140
	v_add_f32_e32 v140, v152, v153
	v_mov_b32_e32 v152, v165
	v_mov_b32_e32 v153, v166
	v_mov_b32_e32 v165, v167
	v_fmamk_f32 v140, v140, 0x3a800000, v148
	v_pk_add_f32 v[152:153], v[152:153], v[164:165]
	v_rsq_f32_e32 v149, v140
	v_add_f32_e32 v140, v152, v153
	v_mul_f32_e32 v153, 0xbfb8aa3b, v170
	v_mul_f32_e32 v156, v119, v153
	v_exp_f32_e32 v157, v156
	v_mul_f32_e32 v156, v115, v153
	v_mul_f32_e32 v155, v114, v153
	v_exp_f32_e32 v158, v156
	v_mul_f32_e32 v156, v120, v153
	v_exp_f32_e32 v155, v155
	v_exp_f32_e32 v159, v156
	v_mul_f32_e32 v156, v116, v153
	v_mul_f32_e32 v154, v118, v153
	v_exp_f32_e32 v160, v156
	v_mul_f32_e32 v156, v121, v153
	v_exp_f32_e32 v154, v154
	v_exp_f32_e32 v161, v156
	v_mul_f32_e32 v153, v117, v153
	v_exp_f32_e32 v153, v153
	v_add_f32_e32 v155, 1.0, v155
	v_rcp_f32_e32 v156, v155
	v_add_f32_e32 v155, 1.0, v157
	v_add_f32_e32 v157, 1.0, v158
	v_add_f32_e32 v158, 1.0, v159
	v_add_f32_e32 v159, 1.0, v160
	v_add_f32_e32 v154, 1.0, v154
	v_rcp_f32_e32 v160, v159
	v_add_f32_e32 v159, 1.0, v161
	v_rcp_f32_e32 v154, v154
	v_rcp_f32_e32 v155, v155
	v_rcp_f32_e32 v157, v157
	v_rcp_f32_e32 v158, v158
	v_rcp_f32_e32 v159, v159
	v_add_f32_e32 v153, 1.0, v153
	s_add_i32 s2, s2, s59
	v_rcp_f32_e32 v161, v153
	v_add_u32_e32 v141, s2, v141
	s_lshl_b32 s2, s60, 7
	s_or_b32 s2, s2, s61
	v_mul_f32_e32 v152, v170, v170
	v_lshl_add_u32 v150, v150, 3, s2
	v_pk_mul_f32 v[120:121], v[120:121], v[128:129]
	v_pk_mul_f32 v[118:119], v[118:119], v[126:127]
	v_pk_mul_f32 v[126:127], v[152:153], v[154:155] op_sel_hi:[0,1]
	v_pk_mul_f32 v[128:129], v[152:153], v[158:159] op_sel_hi:[0,1]
	v_pk_mul_f32 v[114:115], v[114:115], v[122:123]
	v_pk_mul_f32 v[122:123], v[152:153], v[156:157] op_sel_hi:[0,1]
	v_readlane_b32 s2, v255, 0
	v_pk_mul_f32 v[120:121], v[120:121], v[128:129]
	v_pk_mul_f32 v[118:119], v[118:119], v[126:127]
	v_pk_mul_f32 v[116:117], v[116:117], v[124:125]
	v_pk_mul_f32 v[124:125], v[152:153], v[160:161] op_sel_hi:[0,1]
	v_pk_mul_f32 v[114:115], v[114:115], v[122:123]
	v_readlane_b32 s3, v255, 1
	s_waitcnt lgkmcnt(0)
	v_ashrrev_i32_e32 v151, 31, v150
	v_pk_mul_f32 v[116:117], v[116:117], v[124:125]
	v_cvt_pk_bf16_f32 v118, v118, v119
	v_cvt_pk_bf16_f32 v119, v120, v121
	v_cvt_pk_bf16_f32 v120, v114, v115
	v_mov_b64_e32 v[114:115], s[2:3]
	v_cvt_pk_bf16_f32 v121, v116, v117
	v_mad_i64_i32 v[122:123], s[2:3], v141, s50, v[114:115]
	v_lshlrev_b64 v[116:117], 1, v[150:151]
	v_lshl_add_u64 v[122:123], v[122:123], 0, v[116:117]
	s_cmp_eq_u32 s98, 1
	s_cbranch_scc1 .Lwt_0
	global_store_dwordx4 v[122:123], v[118:121], off
	s_branch .Lwtd_0
.Lwt_0:
	global_store_dwordx4 v[122:123], v[118:121], off sc1
.Lwtd_0:
	v_fmamk_f32 v140, v140, 0x3a800000, v148
	v_rsq_f32_e32 v140, v140
	v_mul_f32_e32 v120, 0xbfb8aa3b, v171
	v_mul_f32_e32 v121, v102, v120
	v_mul_f32_e32 v122, v98, v120
	v_exp_f32_e32 v121, v121
	v_exp_f32_e32 v122, v122
	v_mul_f32_e32 v123, v103, v120
	v_mul_f32_e32 v124, v99, v120
	v_mul_f32_e32 v125, v104, v120
	v_mul_f32_e32 v126, v100, v120
	v_exp_f32_e32 v123, v123
	v_exp_f32_e32 v124, v124
	v_exp_f32_e32 v125, v125
	v_exp_f32_e32 v126, v126
	v_mul_f32_e32 v127, v105, v120
	v_mul_f32_e32 v120, v101, v120
	v_exp_f32_e32 v127, v127
	v_exp_f32_e32 v128, v120
	v_add_f32_e32 v120, 1.0, v121
	v_add_f32_e32 v121, 1.0, v122
	v_rcp_f32_e32 v122, v121
	v_add_f32_e32 v121, 1.0, v123
	v_add_f32_e32 v123, 1.0, v124
	v_add_f32_e32 v124, 1.0, v125
	v_add_f32_e32 v125, 1.0, v126
	v_rcp_f32_e32 v120, v120
	v_rcp_f32_e32 v121, v121
	v_rcp_f32_e32 v126, v125
	v_add_f32_e32 v125, 1.0, v127
	v_add_f32_e32 v127, 1.0, v128
	v_rcp_f32_e32 v123, v123
	v_rcp_f32_e32 v127, v127
	v_rcp_f32_e32 v124, v124
	v_rcp_f32_e32 v125, v125
	v_add_u32_e32 v119, 16, v141
	v_mul_f32_e32 v118, v171, v171
	v_pk_mul_f32 v[102:103], v[102:103], v[110:111]
	v_pk_mul_f32 v[110:111], v[118:119], v[120:121] op_sel_hi:[0,1]
	v_pk_mul_f32 v[102:103], v[102:103], v[110:111]
	v_pk_mul_f32 v[100:101], v[100:101], v[108:109]
	v_pk_mul_f32 v[98:99], v[98:99], v[106:107]
	v_pk_mul_f32 v[106:107], v[118:119], v[122:123] op_sel_hi:[0,1]
	v_pk_mul_f32 v[108:109], v[118:119], v[126:127] op_sel_hi:[0,1]
	v_pk_mul_f32 v[104:105], v[104:105], v[112:113]
	v_pk_mul_f32 v[112:113], v[118:119], v[124:125] op_sel_hi:[0,1]
	v_pk_mul_f32 v[108:109], v[100:101], v[108:109]
	v_pk_mul_f32 v[100:101], v[98:99], v[106:107]
	v_cvt_pk_bf16_f32 v98, v102, v103
	v_mad_i64_i32 v[102:103], s[2:3], v119, s50, v[114:115]
	v_pk_mul_f32 v[104:105], v[104:105], v[112:113]
	v_lshl_add_u64 v[102:103], v[102:103], 0, v[116:117]
	v_cvt_pk_bf16_f32 v99, v104, v105
	v_cvt_pk_bf16_f32 v100, v100, v101
	v_cvt_pk_bf16_f32 v101, v108, v109
	s_cmp_eq_u32 s98, 1
	s_cbranch_scc1 .Lwt_1
	global_store_dwordx4 v[102:103], v[98:101], off
	s_branch .Lwtd_1
.Lwt_1:
	global_store_dwordx4 v[102:103], v[98:101], off sc1
.Lwtd_1:
	s_andn2_b64 vcc, exec, s[0:1]
	s_nop 0
	v_mul_f32_e32 v100, 0xbfb8aa3b, v172
	v_mul_f32_e32 v101, v86, v100
	v_mul_f32_e32 v102, v82, v100
	v_exp_f32_e32 v101, v101
	v_exp_f32_e32 v102, v102
	v_mul_f32_e32 v103, v87, v100
	v_mul_f32_e32 v104, v83, v100
	v_mul_f32_e32 v105, v88, v100
	v_mul_f32_e32 v106, v84, v100
	v_exp_f32_e32 v103, v103
	v_exp_f32_e32 v104, v104
	v_exp_f32_e32 v105, v105
	v_exp_f32_e32 v106, v106
	v_mul_f32_e32 v107, v89, v100
	v_mul_f32_e32 v100, v85, v100
	v_exp_f32_e32 v107, v107
	v_exp_f32_e32 v108, v100
	v_add_f32_e32 v100, 1.0, v101
	v_add_f32_e32 v101, 1.0, v102
	v_rcp_f32_e32 v102, v101
	v_add_f32_e32 v101, 1.0, v103
	v_add_f32_e32 v103, 1.0, v104
	v_add_f32_e32 v104, 1.0, v105
	v_add_f32_e32 v105, 1.0, v106
	v_rcp_f32_e32 v100, v100
	v_rcp_f32_e32 v101, v101
	v_rcp_f32_e32 v106, v105
	v_add_f32_e32 v105, 1.0, v107
	v_add_f32_e32 v107, 1.0, v108
	v_rcp_f32_e32 v103, v103
	v_rcp_f32_e32 v107, v107
	v_rcp_f32_e32 v104, v104
	v_rcp_f32_e32 v105, v105
	v_add_u32_e32 v99, 32, v141
	v_mul_f32_e32 v98, v172, v172
	v_pk_mul_f32 v[86:87], v[86:87], v[94:95]
	v_pk_mul_f32 v[94:95], v[98:99], v[100:101] op_sel_hi:[0,1]
	v_pk_mul_f32 v[86:87], v[86:87], v[94:95]
	v_pk_mul_f32 v[84:85], v[84:85], v[92:93]
	v_pk_mul_f32 v[82:83], v[82:83], v[90:91]
	v_pk_mul_f32 v[90:91], v[98:99], v[102:103] op_sel_hi:[0,1]
	v_pk_mul_f32 v[92:93], v[98:99], v[106:107] op_sel_hi:[0,1]
	v_pk_mul_f32 v[88:89], v[88:89], v[96:97]
	v_pk_mul_f32 v[96:97], v[98:99], v[104:105] op_sel_hi:[0,1]
	v_pk_mul_f32 v[92:93], v[84:85], v[92:93]
	v_pk_mul_f32 v[84:85], v[82:83], v[90:91]
	v_cvt_pk_bf16_f32 v82, v86, v87
	v_mad_i64_i32 v[86:87], s[2:3], v99, s50, v[114:115]
	v_pk_mul_f32 v[88:89], v[88:89], v[96:97]
	v_lshl_add_u64 v[86:87], v[86:87], 0, v[116:117]
	v_cvt_pk_bf16_f32 v83, v88, v89
	v_cvt_pk_bf16_f32 v84, v84, v85
	v_cvt_pk_bf16_f32 v85, v92, v93
	s_cmp_eq_u32 s98, 1
	s_cbranch_scc1 .Lwt_2
	global_store_dwordx4 v[86:87], v[82:85], off
	s_branch .Lwtd_2
.Lwt_2:
	global_store_dwordx4 v[86:87], v[82:85], off sc1
.Lwtd_2:
	s_nop 1
	v_mul_f32_e32 v84, 0xbfb8aa3b, v173
	v_mul_f32_e32 v85, v70, v84
	v_mul_f32_e32 v86, v62, v84
	v_exp_f32_e32 v85, v85
	v_exp_f32_e32 v86, v86
	v_mul_f32_e32 v87, v71, v84
	v_mul_f32_e32 v88, v63, v84
	v_mul_f32_e32 v89, v72, v84
	v_mul_f32_e32 v90, v64, v84
	v_exp_f32_e32 v87, v87
	v_exp_f32_e32 v88, v88
	v_exp_f32_e32 v89, v89
	v_exp_f32_e32 v90, v90
	v_mul_f32_e32 v91, v73, v84
	v_mul_f32_e32 v84, v65, v84
	v_exp_f32_e32 v91, v91
	v_exp_f32_e32 v92, v84
	v_add_f32_e32 v84, 1.0, v85
	v_add_f32_e32 v85, 1.0, v86
	v_rcp_f32_e32 v86, v85
	v_add_f32_e32 v85, 1.0, v87
	v_add_f32_e32 v87, 1.0, v88
	v_add_f32_e32 v88, 1.0, v89
	v_add_f32_e32 v89, 1.0, v90
	v_rcp_f32_e32 v84, v84
	v_rcp_f32_e32 v85, v85
	v_rcp_f32_e32 v90, v89
	v_add_f32_e32 v89, 1.0, v91
	v_add_f32_e32 v91, 1.0, v92
	v_rcp_f32_e32 v87, v87
	v_rcp_f32_e32 v91, v91
	v_rcp_f32_e32 v88, v88
	v_rcp_f32_e32 v89, v89
	v_add_u32_e32 v83, 48, v141
	v_mul_f32_e32 v82, v173, v173
	v_pk_mul_f32 v[70:71], v[70:71], v[78:79]
	v_pk_mul_f32 v[78:79], v[82:83], v[84:85] op_sel_hi:[0,1]
	v_pk_mul_f32 v[70:71], v[70:71], v[78:79]
	v_pk_mul_f32 v[64:65], v[64:65], v[76:77]
	v_pk_mul_f32 v[62:63], v[62:63], v[74:75]
	v_pk_mul_f32 v[74:75], v[82:83], v[86:87] op_sel_hi:[0,1]
	v_pk_mul_f32 v[76:77], v[82:83], v[90:91] op_sel_hi:[0,1]
	v_pk_mul_f32 v[72:73], v[72:73], v[80:81]
	v_pk_mul_f32 v[80:81], v[82:83], v[88:89] op_sel_hi:[0,1]
	v_pk_mul_f32 v[76:77], v[64:65], v[76:77]
	v_pk_mul_f32 v[64:65], v[62:63], v[74:75]
	v_cvt_pk_bf16_f32 v62, v70, v71
	v_mad_i64_i32 v[70:71], s[2:3], v83, s50, v[114:115]
	v_pk_mul_f32 v[72:73], v[72:73], v[80:81]
	v_lshl_add_u64 v[70:71], v[70:71], 0, v[116:117]
	v_cvt_pk_bf16_f32 v63, v72, v73
	v_cvt_pk_bf16_f32 v64, v64, v65
	v_cvt_pk_bf16_f32 v65, v76, v77
	s_cmp_eq_u32 s98, 1
	s_cbranch_scc1 .Lwt_3
	global_store_dwordx4 v[70:71], v[62:65], off
	s_branch .Lwtd_3
.Lwt_3:
	global_store_dwordx4 v[70:71], v[62:65], off sc1
.Lwtd_3:
	s_nop 1
	v_mul_f32_e32 v64, 0xbfb8aa3b, v168
	v_mul_f32_e32 v65, v54, v64
	v_mul_f32_e32 v70, v50, v64
	v_exp_f32_e32 v65, v65
	v_exp_f32_e32 v70, v70
	v_mul_f32_e32 v71, v55, v64
	v_mul_f32_e32 v72, v51, v64
	v_mul_f32_e32 v73, v56, v64
	v_mul_f32_e32 v74, v52, v64
	v_exp_f32_e32 v71, v71
	v_exp_f32_e32 v72, v72
	v_exp_f32_e32 v73, v73
	v_exp_f32_e32 v74, v74
	v_mul_f32_e32 v75, v57, v64
	v_mul_f32_e32 v64, v53, v64
	v_exp_f32_e32 v75, v75
	v_exp_f32_e32 v76, v64
	v_add_f32_e32 v64, 1.0, v65
	v_add_f32_e32 v65, 1.0, v70
	v_rcp_f32_e32 v70, v65
	v_add_f32_e32 v65, 1.0, v71
	v_add_f32_e32 v71, 1.0, v72
	v_add_f32_e32 v72, 1.0, v73
	v_add_f32_e32 v73, 1.0, v74
	v_rcp_f32_e32 v64, v64
	v_rcp_f32_e32 v65, v65
	v_rcp_f32_e32 v74, v73
	v_add_f32_e32 v73, 1.0, v75
	v_add_f32_e32 v75, 1.0, v76
	v_rcp_f32_e32 v71, v71
	v_rcp_f32_e32 v75, v75
	v_rcp_f32_e32 v72, v72
	v_rcp_f32_e32 v73, v73
	v_add_u32_e32 v63, 0x80, v141
	v_mul_f32_e32 v62, v168, v168
	v_pk_mul_f32 v[54:55], v[54:55], v[66:67]
	v_pk_mul_f32 v[64:65], v[62:63], v[64:65] op_sel_hi:[0,1]
	v_pk_mul_f32 v[54:55], v[54:55], v[64:65]
	v_pk_mul_f32 v[52:53], v[52:53], v[60:61]
	v_pk_mul_f32 v[50:51], v[50:51], v[58:59]
	v_pk_mul_f32 v[58:59], v[62:63], v[70:71] op_sel_hi:[0,1]
	v_pk_mul_f32 v[60:61], v[62:63], v[74:75] op_sel_hi:[0,1]
	v_pk_mul_f32 v[56:57], v[56:57], v[68:69]
	v_pk_mul_f32 v[66:67], v[62:63], v[72:73] op_sel_hi:[0,1]
	v_pk_mul_f32 v[60:61], v[52:53], v[60:61]
	v_pk_mul_f32 v[52:53], v[50:51], v[58:59]
	v_cvt_pk_bf16_f32 v50, v54, v55
	v_mad_i64_i32 v[54:55], s[2:3], v63, s50, v[114:115]
	v_pk_mul_f32 v[56:57], v[56:57], v[66:67]
	v_lshl_add_u64 v[54:55], v[54:55], 0, v[116:117]
	v_cvt_pk_bf16_f32 v51, v56, v57
	v_cvt_pk_bf16_f32 v52, v52, v53
	v_cvt_pk_bf16_f32 v53, v60, v61
	s_cmp_eq_u32 s98, 1
	s_cbranch_scc1 .Lwt_4
	global_store_dwordx4 v[54:55], v[50:53], off
	s_branch .Lwtd_4
.Lwt_4:
	global_store_dwordx4 v[54:55], v[50:53], off sc1
.Lwtd_4:
	s_nop 1
	v_mul_f32_e32 v52, 0xbfb8aa3b, v169
	v_mul_f32_e32 v53, v38, v52
	v_mul_f32_e32 v54, v34, v52
	v_exp_f32_e32 v53, v53
	v_exp_f32_e32 v54, v54
	v_mul_f32_e32 v55, v39, v52
	v_mul_f32_e32 v56, v35, v52
	v_mul_f32_e32 v57, v40, v52
	v_mul_f32_e32 v58, v36, v52
	v_exp_f32_e32 v55, v55
	v_exp_f32_e32 v56, v56
	v_exp_f32_e32 v57, v57
	v_exp_f32_e32 v58, v58
	v_mul_f32_e32 v59, v41, v52
	v_mul_f32_e32 v52, v37, v52
	v_exp_f32_e32 v59, v59
	v_exp_f32_e32 v60, v52
	v_add_f32_e32 v52, 1.0, v53
	v_add_f32_e32 v53, 1.0, v54
	v_rcp_f32_e32 v54, v53
	v_add_f32_e32 v53, 1.0, v55
	v_add_f32_e32 v55, 1.0, v56
	v_add_f32_e32 v56, 1.0, v57
	v_add_f32_e32 v57, 1.0, v58
	v_rcp_f32_e32 v52, v52
	v_rcp_f32_e32 v53, v53
	v_rcp_f32_e32 v58, v57
	v_add_f32_e32 v57, 1.0, v59
	v_add_f32_e32 v59, 1.0, v60
	v_rcp_f32_e32 v55, v55
	v_rcp_f32_e32 v59, v59
	v_rcp_f32_e32 v56, v56
	v_rcp_f32_e32 v57, v57
	v_add_u32_e32 v51, 0x90, v141
	v_mul_f32_e32 v50, v169, v169
	v_pk_mul_f32 v[38:39], v[38:39], v[46:47]
	v_pk_mul_f32 v[46:47], v[50:51], v[52:53] op_sel_hi:[0,1]
	v_pk_mul_f32 v[38:39], v[38:39], v[46:47]
	v_pk_mul_f32 v[36:37], v[36:37], v[44:45]
	v_pk_mul_f32 v[34:35], v[34:35], v[42:43]
	v_pk_mul_f32 v[42:43], v[50:51], v[54:55] op_sel_hi:[0,1]
	v_pk_mul_f32 v[44:45], v[50:51], v[58:59] op_sel_hi:[0,1]
	v_pk_mul_f32 v[40:41], v[40:41], v[48:49]
	v_pk_mul_f32 v[48:49], v[50:51], v[56:57] op_sel_hi:[0,1]
	v_pk_mul_f32 v[44:45], v[36:37], v[44:45]
	v_pk_mul_f32 v[36:37], v[34:35], v[42:43]
	v_cvt_pk_bf16_f32 v34, v38, v39
	v_mad_i64_i32 v[38:39], s[2:3], v51, s50, v[114:115]
	v_pk_mul_f32 v[40:41], v[40:41], v[48:49]
	v_lshl_add_u64 v[38:39], v[38:39], 0, v[116:117]
	v_cvt_pk_bf16_f32 v35, v40, v41
	v_cvt_pk_bf16_f32 v36, v36, v37
	v_cvt_pk_bf16_f32 v37, v44, v45
	s_cmp_eq_u32 s98, 1
	s_cbranch_scc1 .Lwt_5
	global_store_dwordx4 v[38:39], v[34:37], off
	s_branch .Lwtd_5
.Lwt_5:
	global_store_dwordx4 v[38:39], v[34:37], off sc1
.Lwtd_5:
	s_nop 1
	v_mul_f32_e32 v36, 0xbfb8aa3b, v149
	v_mul_f32_e32 v37, v22, v36
	v_mul_f32_e32 v38, v18, v36
	v_exp_f32_e32 v37, v37
	v_exp_f32_e32 v38, v38
	v_mul_f32_e32 v39, v23, v36
	v_mul_f32_e32 v40, v19, v36
	v_mul_f32_e32 v41, v24, v36
	v_mul_f32_e32 v42, v20, v36
	v_exp_f32_e32 v39, v39
	v_exp_f32_e32 v40, v40
	v_exp_f32_e32 v41, v41
	v_exp_f32_e32 v42, v42
	v_mul_f32_e32 v43, v25, v36
	v_mul_f32_e32 v36, v21, v36
	v_exp_f32_e32 v43, v43
	v_exp_f32_e32 v44, v36
	v_add_f32_e32 v36, 1.0, v37
	v_add_f32_e32 v37, 1.0, v38
	v_rcp_f32_e32 v38, v37
	v_add_f32_e32 v37, 1.0, v39
	v_add_f32_e32 v39, 1.0, v40
	v_add_f32_e32 v40, 1.0, v41
	v_add_f32_e32 v41, 1.0, v42
	v_rcp_f32_e32 v36, v36
	v_rcp_f32_e32 v37, v37
	v_rcp_f32_e32 v42, v41
	v_add_f32_e32 v41, 1.0, v43
	v_add_f32_e32 v43, 1.0, v44
	v_rcp_f32_e32 v39, v39
	v_rcp_f32_e32 v43, v43
	v_rcp_f32_e32 v40, v40
	v_rcp_f32_e32 v41, v41
	v_add_u32_e32 v35, 0xa0, v141
	v_mul_f32_e32 v34, v149, v149
	v_pk_mul_f32 v[22:23], v[22:23], v[30:31]
	v_pk_mul_f32 v[30:31], v[34:35], v[36:37] op_sel_hi:[0,1]
	v_pk_mul_f32 v[22:23], v[22:23], v[30:31]
	v_pk_mul_f32 v[20:21], v[20:21], v[28:29]
	v_pk_mul_f32 v[18:19], v[18:19], v[26:27]
	v_pk_mul_f32 v[26:27], v[34:35], v[38:39] op_sel_hi:[0,1]
	v_pk_mul_f32 v[28:29], v[34:35], v[42:43] op_sel_hi:[0,1]
	v_pk_mul_f32 v[24:25], v[24:25], v[32:33]
	v_pk_mul_f32 v[32:33], v[34:35], v[40:41] op_sel_hi:[0,1]
	v_pk_mul_f32 v[28:29], v[20:21], v[28:29]
	v_pk_mul_f32 v[20:21], v[18:19], v[26:27]
	v_cvt_pk_bf16_f32 v18, v22, v23
	v_mad_i64_i32 v[22:23], s[2:3], v35, s50, v[114:115]
	v_pk_mul_f32 v[24:25], v[24:25], v[32:33]
	v_lshl_add_u64 v[22:23], v[22:23], 0, v[116:117]
	v_cvt_pk_bf16_f32 v19, v24, v25
	v_cvt_pk_bf16_f32 v20, v20, v21
	v_cvt_pk_bf16_f32 v21, v28, v29
	s_cmp_eq_u32 s98, 1
	s_cbranch_scc1 .Lwt_6
	global_store_dwordx4 v[22:23], v[18:21], off
	s_branch .Lwtd_6
.Lwt_6:
	global_store_dwordx4 v[22:23], v[18:21], off sc1
.Lwtd_6:
	s_nop 1
	v_mul_f32_e32 v20, 0xbfb8aa3b, v140
	v_mul_f32_e32 v21, v6, v20
	v_mul_f32_e32 v22, v2, v20
	v_exp_f32_e32 v21, v21
	v_exp_f32_e32 v22, v22
	v_mul_f32_e32 v23, v7, v20
	v_mul_f32_e32 v24, v3, v20
	v_mul_f32_e32 v25, v8, v20
	v_mul_f32_e32 v26, v4, v20
	v_exp_f32_e32 v23, v23
	v_exp_f32_e32 v24, v24
	v_exp_f32_e32 v25, v25
	v_exp_f32_e32 v26, v26
	v_mul_f32_e32 v27, v9, v20
	v_mul_f32_e32 v20, v5, v20
	v_exp_f32_e32 v27, v27
	v_exp_f32_e32 v28, v20
	v_add_f32_e32 v20, 1.0, v21
	v_add_f32_e32 v21, 1.0, v22
	v_rcp_f32_e32 v22, v21
	v_add_f32_e32 v21, 1.0, v23
	v_add_f32_e32 v23, 1.0, v24
	v_add_f32_e32 v24, 1.0, v25
	v_add_f32_e32 v25, 1.0, v26
	v_rcp_f32_e32 v20, v20
	v_rcp_f32_e32 v21, v21
	v_rcp_f32_e32 v26, v25
	v_add_f32_e32 v25, 1.0, v27
	v_add_f32_e32 v27, 1.0, v28
	v_rcp_f32_e32 v23, v23
	v_rcp_f32_e32 v27, v27
	v_add_u32_e32 v19, 0xb0, v141
	v_mul_f32_e32 v18, v140, v140
	v_rcp_f32_e32 v24, v24
	v_rcp_f32_e32 v25, v25
	v_pk_mul_f32 v[6:7], v[6:7], v[14:15]
	v_pk_mul_f32 v[14:15], v[18:19], v[20:21] op_sel_hi:[0,1]
	v_pk_mul_f32 v[6:7], v[6:7], v[14:15]
	v_pk_mul_f32 v[4:5], v[4:5], v[12:13]
	v_pk_mul_f32 v[2:3], v[2:3], v[10:11]
	v_pk_mul_f32 v[10:11], v[18:19], v[22:23] op_sel_hi:[0,1]
	v_pk_mul_f32 v[12:13], v[18:19], v[26:27] op_sel_hi:[0,1]
	v_pk_mul_f32 v[12:13], v[4:5], v[12:13]
	v_pk_mul_f32 v[4:5], v[2:3], v[10:11]
	v_cvt_pk_bf16_f32 v2, v6, v7
	v_mad_i64_i32 v[6:7], s[2:3], v19, s50, v[114:115]
	v_pk_mul_f32 v[8:9], v[8:9], v[16:17]
	v_pk_mul_f32 v[16:17], v[18:19], v[24:25] op_sel_hi:[0,1]
	v_lshl_add_u64 v[6:7], v[6:7], 0, v[116:117]
	v_pk_mul_f32 v[8:9], v[8:9], v[16:17]
	s_nop 0
	v_cvt_pk_bf16_f32 v3, v8, v9
	v_cvt_pk_bf16_f32 v4, v4, v5
	v_cvt_pk_bf16_f32 v5, v12, v13
	s_cmp_eq_u32 s98, 1
	s_cbranch_scc1 .Lwt_7
	global_store_dwordx4 v[6:7], v[2:5], off
	s_branch .Lwtd_7
.Lwt_7:
	global_store_dwordx4 v[6:7], v[2:5], off sc1
.Lwtd_7:
	s_cbranch_vccnz .LBB0_211
	v_readlane_b32 s0, v255, 13
	v_readlane_b32 s1, v255, 14
	s_andn2_b64 vcc, exec, s[0:1]
	s_cbranch_vccnz .LBB0_194
	s_barrier
	s_branch .LBB0_194

.LBB0_1721:
	v_cndmask_b32_e64 v140, 0, 1, s[4:5]
	s_and_b32 s3, s85, 1
	v_mov_b32_e32 v141, v1
	v_mov_b32_e32 v150, v143
	v_cmp_ne_u32_e64 s[6:7], 1, v140
	s_cmp_lg_u64 s[4:5], 0
	s_cselect_b32 s98, 1, 0
	s_andn2_b64 vcc, exec, s[4:5]
	s_mov_b64 s[4:5], -1
	s_cbranch_vccnz .LBB0_1723
	s_lshl_b32 s12, s3, 12
	s_mov_b64 s[4:5], 0

.LBB0_1725:
	s_add_u32 s4, s50, 0xfffffe00
	s_addc_u32 s5, s51, -1
	s_add_i32 s3, s88, s12
	v_lshl_add_u32 v140, v141, 4, s3
	ds_read_b128 v[152:155], v140
	ds_read_b128 v[156:159], v140 offset:256
	ds_read_b128 v[160:163], v140 offset:512
	ds_read_b128 v[164:167], v140 offset:768
	s_waitcnt lgkmcnt(0)
	s_waitcnt lgkmcnt(0)
	v_mov_b32_e32 v168, v153
	v_mov_b32_e32 v169, v154
	v_mov_b32_e32 v153, v155
	v_pk_add_f32 v[152:153], v[168:169], v[152:153]
	s_lshl_b32 s3, s10, 8
	v_add_f32_e32 v149, v152, v153
	v_mov_b32_e32 v152, v157
	v_mov_b32_e32 v153, v158
	v_mov_b32_e32 v157, v159
	v_fmamk_f32 v149, v149, 0x3a800000, v148
	v_pk_add_f32 v[152:153], v[152:153], v[156:157]
	v_rsq_f32_e32 v170, v149
	v_add_f32_e32 v149, v152, v153
	v_mov_b32_e32 v152, v161
	v_mov_b32_e32 v153, v162
	v_mov_b32_e32 v161, v163
	v_fmamk_f32 v149, v149, 0x3a800000, v148
	v_pk_add_f32 v[152:153], v[152:153], v[160:161]
	v_rsq_f32_e32 v171, v149
	v_add_f32_e32 v149, v152, v153
	v_mov_b32_e32 v152, v165
	v_mov_b32_e32 v153, v166
	v_mov_b32_e32 v165, v167
	v_fmamk_f32 v149, v149, 0x3a800000, v148
	v_pk_add_f32 v[152:153], v[152:153], v[164:165]
	v_rsq_f32_e32 v172, v149
	v_add_f32_e32 v149, v152, v153
	ds_read_b128 v[152:155], v140 offset:2048
	ds_read_b128 v[156:159], v140 offset:2304
	ds_read_b128 v[160:163], v140 offset:2560
	ds_read_b128 v[164:167], v140 offset:2816
	v_fmamk_f32 v149, v149, 0x3a800000, v148
	s_waitcnt lgkmcnt(0)
	v_mov_b32_e32 v168, v153
	v_mov_b32_e32 v169, v154
	v_mov_b32_e32 v153, v155
	v_pk_add_f32 v[152:153], v[168:169], v[152:153]
	v_rsq_f32_e32 v173, v149
	v_add_f32_e32 v140, v152, v153
	v_mov_b32_e32 v152, v157
	v_mov_b32_e32 v153, v158
	v_mov_b32_e32 v157, v159
	v_fmamk_f32 v140, v140, 0x3a800000, v148
	v_pk_add_f32 v[152:153], v[152:153], v[156:157]
	v_rsq_f32_e32 v168, v140
	v_add_f32_e32 v140, v152, v153
	v_mov_b32_e32 v152, v161
	v_mov_b32_e32 v153, v162
	v_mov_b32_e32 v161, v163
	v_fmamk_f32 v140, v140, 0x3a800000, v148
	v_pk_add_f32 v[152:153], v[152:153], v[160:161]
	v_rsq_f32_e32 v169, v140
	v_add_f32_e32 v140, v152, v153
	v_mov_b32_e32 v152, v165
	v_mov_b32_e32 v153, v166
	v_mov_b32_e32 v165, v167
	v_fmamk_f32 v140, v140, 0x3a800000, v148
	v_pk_add_f32 v[152:153], v[152:153], v[164:165]
	v_rsq_f32_e32 v149, v140
	v_add_f32_e32 v140, v152, v153
	v_mul_f32_e32 v153, 0xbfb8aa3b, v170
	v_mul_f32_e32 v156, v119, v153
	v_exp_f32_e32 v157, v156
	v_mul_f32_e32 v156, v115, v153
	v_mul_f32_e32 v155, v114, v153
	v_exp_f32_e32 v158, v156
	v_mul_f32_e32 v156, v120, v153
	v_exp_f32_e32 v155, v155
	v_exp_f32_e32 v159, v156
	v_mul_f32_e32 v156, v116, v153
	v_mul_f32_e32 v154, v118, v153
	v_exp_f32_e32 v160, v156
	v_mul_f32_e32 v156, v121, v153
	v_exp_f32_e32 v154, v154
	v_exp_f32_e32 v161, v156
	v_mul_f32_e32 v153, v117, v153
	v_exp_f32_e32 v153, v153
	v_add_f32_e32 v155, 1.0, v155
	v_rcp_f32_e32 v156, v155
	v_add_f32_e32 v155, 1.0, v157
	v_add_f32_e32 v157, 1.0, v158
	v_add_f32_e32 v158, 1.0, v159
	v_add_f32_e32 v159, 1.0, v160
	v_add_f32_e32 v154, 1.0, v154
	v_rcp_f32_e32 v160, v159
	v_add_f32_e32 v159, 1.0, v161
	v_rcp_f32_e32 v154, v154
	v_rcp_f32_e32 v155, v155
	v_rcp_f32_e32 v157, v157
	v_rcp_f32_e32 v158, v158
	v_rcp_f32_e32 v159, v159
	v_add_f32_e32 v153, 1.0, v153
	v_rcp_f32_e32 v161, v153
	s_add_i32 s3, s3, s82
	v_add_u32_e32 v141, s3, v141
	s_lshl_b32 s3, s83, 7
	v_mul_f32_e32 v152, v170, v170
	s_or_b32 s3, s3, s84
	v_pk_mul_f32 v[120:121], v[120:121], v[128:129]
	v_pk_mul_f32 v[118:119], v[118:119], v[126:127]
	v_pk_mul_f32 v[126:127], v[152:153], v[154:155] op_sel_hi:[0,1]
	v_pk_mul_f32 v[128:129], v[152:153], v[158:159] op_sel_hi:[0,1]
	v_pk_mul_f32 v[114:115], v[114:115], v[122:123]
	v_pk_mul_f32 v[122:123], v[152:153], v[156:157] op_sel_hi:[0,1]
	v_readlane_b32 s12, v255, 0
	v_lshl_add_u32 v150, v150, 3, s3
	v_pk_mul_f32 v[120:121], v[120:121], v[128:129]
	v_pk_mul_f32 v[118:119], v[118:119], v[126:127]
	v_pk_mul_f32 v[116:117], v[116:117], v[124:125]
	v_pk_mul_f32 v[124:125], v[152:153], v[160:161] op_sel_hi:[0,1]
	v_pk_mul_f32 v[114:115], v[114:115], v[122:123]
	v_readlane_b32 s13, v255, 1
	s_waitcnt lgkmcnt(0)
	v_ashrrev_i32_e32 v151, 31, v150
	v_pk_mul_f32 v[116:117], v[116:117], v[124:125]
	v_cvt_pk_bf16_f32 v118, v118, v119
	v_cvt_pk_bf16_f32 v119, v120, v121
	v_cvt_pk_bf16_f32 v120, v114, v115
	v_mov_b64_e32 v[114:115], s[12:13]
	v_cvt_pk_bf16_f32 v121, v116, v117
	v_mad_i64_i32 v[122:123], s[12:13], v141, s91, v[114:115]
	v_lshlrev_b64 v[116:117], 1, v[150:151]
	v_lshl_add_u64 v[122:123], v[122:123], 0, v[116:117]
	s_cmp_eq_u32 s98, 1
	s_cbranch_scc1 .Lwt_8
	global_store_dwordx4 v[122:123], v[118:121], off
	s_branch .Lwtd_8

.Lwtd_8:
	v_fmamk_f32 v140, v140, 0x3a800000, v148
	v_rsq_f32_e32 v140, v140
	v_mul_f32_e32 v120, 0xbfb8aa3b, v171
	v_mul_f32_e32 v121, v102, v120
	v_mul_f32_e32 v122, v98, v120
	v_exp_f32_e32 v121, v121
	v_exp_f32_e32 v122, v122
	v_mul_f32_e32 v123, v103, v120
	v_mul_f32_e32 v124, v99, v120
	v_mul_f32_e32 v125, v104, v120
	v_mul_f32_e32 v126, v100, v120
	v_exp_f32_e32 v123, v123
	v_exp_f32_e32 v124, v124
	v_exp_f32_e32 v125, v125
	v_exp_f32_e32 v126, v126
	v_mul_f32_e32 v127, v105, v120
	v_mul_f32_e32 v120, v101, v120
	v_exp_f32_e32 v127, v127
	v_exp_f32_e32 v128, v120
	v_add_f32_e32 v120, 1.0, v121
	v_add_f32_e32 v121, 1.0, v122
	v_rcp_f32_e32 v122, v121
	v_add_f32_e32 v121, 1.0, v123
	v_add_f32_e32 v123, 1.0, v124
	v_add_f32_e32 v124, 1.0, v125
	v_add_f32_e32 v125, 1.0, v126
	v_rcp_f32_e32 v120, v120
	v_rcp_f32_e32 v121, v121
	v_rcp_f32_e32 v126, v125
	v_add_f32_e32 v125, 1.0, v127
	v_add_f32_e32 v127, 1.0, v128
	v_rcp_f32_e32 v123, v123
	v_rcp_f32_e32 v127, v127
	v_rcp_f32_e32 v124, v124
	v_rcp_f32_e32 v125, v125
	v_add_u32_e32 v119, 16, v141
	v_mul_f32_e32 v118, v171, v171
	v_pk_mul_f32 v[102:103], v[102:103], v[110:111]
	v_pk_mul_f32 v[110:111], v[118:119], v[120:121] op_sel_hi:[0,1]
	v_pk_mul_f32 v[102:103], v[102:103], v[110:111]
	v_pk_mul_f32 v[100:101], v[100:101], v[108:109]
	v_pk_mul_f32 v[98:99], v[98:99], v[106:107]
	v_pk_mul_f32 v[106:107], v[118:119], v[122:123] op_sel_hi:[0,1]
	v_pk_mul_f32 v[108:109], v[118:119], v[126:127] op_sel_hi:[0,1]
	v_pk_mul_f32 v[104:105], v[104:105], v[112:113]
	v_pk_mul_f32 v[112:113], v[118:119], v[124:125] op_sel_hi:[0,1]
	v_pk_mul_f32 v[108:109], v[100:101], v[108:109]
	v_pk_mul_f32 v[100:101], v[98:99], v[106:107]
	v_cvt_pk_bf16_f32 v98, v102, v103
	v_mad_i64_i32 v[102:103], s[12:13], v119, s91, v[114:115]
	v_pk_mul_f32 v[104:105], v[104:105], v[112:113]
	v_lshl_add_u64 v[102:103], v[102:103], 0, v[116:117]
	v_cvt_pk_bf16_f32 v99, v104, v105
	v_cvt_pk_bf16_f32 v100, v100, v101
	v_cvt_pk_bf16_f32 v101, v108, v109
	s_cmp_eq_u32 s98, 1
	s_cbranch_scc1 .Lwt_9
	global_store_dwordx4 v[102:103], v[98:101], off
	s_branch .Lwtd_9

.Lwtd_9:
	s_andn2_b64 vcc, exec, s[0:1]
	s_nop 0
	v_mul_f32_e32 v100, 0xbfb8aa3b, v172
	v_mul_f32_e32 v101, v86, v100
	v_mul_f32_e32 v102, v82, v100
	v_exp_f32_e32 v101, v101
	v_exp_f32_e32 v102, v102
	v_mul_f32_e32 v103, v87, v100
	v_mul_f32_e32 v104, v83, v100
	v_mul_f32_e32 v105, v88, v100
	v_mul_f32_e32 v106, v84, v100
	v_exp_f32_e32 v103, v103
	v_exp_f32_e32 v104, v104
	v_exp_f32_e32 v105, v105
	v_exp_f32_e32 v106, v106
	v_mul_f32_e32 v107, v89, v100
	v_mul_f32_e32 v100, v85, v100
	v_exp_f32_e32 v107, v107
	v_exp_f32_e32 v108, v100
	v_add_f32_e32 v100, 1.0, v101
	v_add_f32_e32 v101, 1.0, v102
	v_rcp_f32_e32 v102, v101
	v_add_f32_e32 v101, 1.0, v103
	v_add_f32_e32 v103, 1.0, v104
	v_add_f32_e32 v104, 1.0, v105
	v_add_f32_e32 v105, 1.0, v106
	v_rcp_f32_e32 v100, v100
	v_rcp_f32_e32 v101, v101
	v_rcp_f32_e32 v106, v105
	v_add_f32_e32 v105, 1.0, v107
	v_add_f32_e32 v107, 1.0, v108
	v_rcp_f32_e32 v103, v103
	v_rcp_f32_e32 v107, v107
	v_rcp_f32_e32 v104, v104
	v_rcp_f32_e32 v105, v105
	v_add_u32_e32 v99, 32, v141
	v_mul_f32_e32 v98, v172, v172
	v_pk_mul_f32 v[86:87], v[86:87], v[94:95]
	v_pk_mul_f32 v[94:95], v[98:99], v[100:101] op_sel_hi:[0,1]
	v_pk_mul_f32 v[86:87], v[86:87], v[94:95]
	v_pk_mul_f32 v[84:85], v[84:85], v[92:93]
	v_pk_mul_f32 v[82:83], v[82:83], v[90:91]
	v_pk_mul_f32 v[90:91], v[98:99], v[102:103] op_sel_hi:[0,1]
	v_pk_mul_f32 v[92:93], v[98:99], v[106:107] op_sel_hi:[0,1]
	v_pk_mul_f32 v[88:89], v[88:89], v[96:97]
	v_pk_mul_f32 v[96:97], v[98:99], v[104:105] op_sel_hi:[0,1]
	v_pk_mul_f32 v[92:93], v[84:85], v[92:93]
	v_pk_mul_f32 v[84:85], v[82:83], v[90:91]
	v_cvt_pk_bf16_f32 v82, v86, v87
	v_mad_i64_i32 v[86:87], s[12:13], v99, s91, v[114:115]
	v_pk_mul_f32 v[88:89], v[88:89], v[96:97]
	v_lshl_add_u64 v[86:87], v[86:87], 0, v[116:117]
	v_cvt_pk_bf16_f32 v83, v88, v89
	v_cvt_pk_bf16_f32 v84, v84, v85
	v_cvt_pk_bf16_f32 v85, v92, v93
	s_cmp_eq_u32 s98, 1
	s_cbranch_scc1 .Lwt_10
	global_store_dwordx4 v[86:87], v[82:85], off
	s_branch .Lwtd_10

.Lwtd_10:
	s_nop 1
	v_mul_f32_e32 v84, 0xbfb8aa3b, v173
	v_mul_f32_e32 v85, v70, v84
	v_mul_f32_e32 v86, v62, v84
	v_exp_f32_e32 v85, v85
	v_exp_f32_e32 v86, v86
	v_mul_f32_e32 v87, v71, v84
	v_mul_f32_e32 v88, v63, v84
	v_mul_f32_e32 v89, v72, v84
	v_mul_f32_e32 v90, v64, v84
	v_exp_f32_e32 v87, v87
	v_exp_f32_e32 v88, v88
	v_exp_f32_e32 v89, v89
	v_exp_f32_e32 v90, v90
	v_mul_f32_e32 v91, v73, v84
	v_mul_f32_e32 v84, v65, v84
	v_exp_f32_e32 v91, v91
	v_exp_f32_e32 v92, v84
	v_add_f32_e32 v84, 1.0, v85
	v_add_f32_e32 v85, 1.0, v86
	v_rcp_f32_e32 v86, v85
	v_add_f32_e32 v85, 1.0, v87
	v_add_f32_e32 v87, 1.0, v88
	v_add_f32_e32 v88, 1.0, v89
	v_add_f32_e32 v89, 1.0, v90
	v_rcp_f32_e32 v84, v84
	v_rcp_f32_e32 v85, v85
	v_rcp_f32_e32 v90, v89
	v_add_f32_e32 v89, 1.0, v91
	v_add_f32_e32 v91, 1.0, v92
	v_rcp_f32_e32 v87, v87
	v_rcp_f32_e32 v91, v91
	v_rcp_f32_e32 v88, v88
	v_rcp_f32_e32 v89, v89
	v_add_u32_e32 v83, 48, v141
	v_mul_f32_e32 v82, v173, v173
	v_pk_mul_f32 v[70:71], v[70:71], v[78:79]
	v_pk_mul_f32 v[78:79], v[82:83], v[84:85] op_sel_hi:[0,1]
	v_pk_mul_f32 v[70:71], v[70:71], v[78:79]
	v_pk_mul_f32 v[64:65], v[64:65], v[76:77]
	v_pk_mul_f32 v[62:63], v[62:63], v[74:75]
	v_pk_mul_f32 v[74:75], v[82:83], v[86:87] op_sel_hi:[0,1]
	v_pk_mul_f32 v[76:77], v[82:83], v[90:91] op_sel_hi:[0,1]
	v_pk_mul_f32 v[72:73], v[72:73], v[80:81]
	v_pk_mul_f32 v[80:81], v[82:83], v[88:89] op_sel_hi:[0,1]
	v_pk_mul_f32 v[76:77], v[64:65], v[76:77]
	v_pk_mul_f32 v[64:65], v[62:63], v[74:75]
	v_cvt_pk_bf16_f32 v62, v70, v71
	v_mad_i64_i32 v[70:71], s[12:13], v83, s91, v[114:115]
	v_pk_mul_f32 v[72:73], v[72:73], v[80:81]
	v_lshl_add_u64 v[70:71], v[70:71], 0, v[116:117]
	v_cvt_pk_bf16_f32 v63, v72, v73
	v_cvt_pk_bf16_f32 v64, v64, v65
	v_cvt_pk_bf16_f32 v65, v76, v77
	s_cmp_eq_u32 s98, 1
	s_cbranch_scc1 .Lwt_11
	global_store_dwordx4 v[70:71], v[62:65], off
	s_branch .Lwtd_11

.Lwtd_11:
	s_nop 1
	v_mul_f32_e32 v64, 0xbfb8aa3b, v168
	v_mul_f32_e32 v65, v54, v64
	v_mul_f32_e32 v70, v50, v64
	v_exp_f32_e32 v65, v65
	v_exp_f32_e32 v70, v70
	v_mul_f32_e32 v71, v55, v64
	v_mul_f32_e32 v72, v51, v64
	v_mul_f32_e32 v73, v56, v64
	v_mul_f32_e32 v74, v52, v64
	v_exp_f32_e32 v71, v71
	v_exp_f32_e32 v72, v72
	v_exp_f32_e32 v73, v73
	v_exp_f32_e32 v74, v74
	v_mul_f32_e32 v75, v57, v64
	v_mul_f32_e32 v64, v53, v64
	v_exp_f32_e32 v75, v75
	v_exp_f32_e32 v76, v64
	v_add_f32_e32 v64, 1.0, v65
	v_add_f32_e32 v65, 1.0, v70
	v_rcp_f32_e32 v70, v65
	v_add_f32_e32 v65, 1.0, v71
	v_add_f32_e32 v71, 1.0, v72
	v_add_f32_e32 v72, 1.0, v73
	v_add_f32_e32 v73, 1.0, v74
	v_rcp_f32_e32 v64, v64
	v_rcp_f32_e32 v65, v65
	v_rcp_f32_e32 v74, v73
	v_add_f32_e32 v73, 1.0, v75
	v_add_f32_e32 v75, 1.0, v76
	v_rcp_f32_e32 v71, v71
	v_rcp_f32_e32 v75, v75
	v_rcp_f32_e32 v72, v72
	v_rcp_f32_e32 v73, v73
	v_add_u32_e32 v63, 0x80, v141
	v_mul_f32_e32 v62, v168, v168
	v_pk_mul_f32 v[54:55], v[54:55], v[66:67]
	v_pk_mul_f32 v[64:65], v[62:63], v[64:65] op_sel_hi:[0,1]
	v_pk_mul_f32 v[54:55], v[54:55], v[64:65]
	v_pk_mul_f32 v[52:53], v[52:53], v[60:61]
	v_pk_mul_f32 v[50:51], v[50:51], v[58:59]
	v_pk_mul_f32 v[58:59], v[62:63], v[70:71] op_sel_hi:[0,1]
	v_pk_mul_f32 v[60:61], v[62:63], v[74:75] op_sel_hi:[0,1]
	v_pk_mul_f32 v[56:57], v[56:57], v[68:69]
	v_pk_mul_f32 v[66:67], v[62:63], v[72:73] op_sel_hi:[0,1]
	v_pk_mul_f32 v[60:61], v[52:53], v[60:61]
	v_pk_mul_f32 v[52:53], v[50:51], v[58:59]
	v_cvt_pk_bf16_f32 v50, v54, v55
	v_mad_i64_i32 v[54:55], s[12:13], v63, s91, v[114:115]
	v_pk_mul_f32 v[56:57], v[56:57], v[66:67]
	v_lshl_add_u64 v[54:55], v[54:55], 0, v[116:117]
	v_cvt_pk_bf16_f32 v51, v56, v57
	v_cvt_pk_bf16_f32 v52, v52, v53
	v_cvt_pk_bf16_f32 v53, v60, v61
	s_cmp_eq_u32 s98, 1
	s_cbranch_scc1 .Lwt_12
	global_store_dwordx4 v[54:55], v[50:53], off
	s_branch .Lwtd_12

.Lwtd_12:
	s_nop 1
	v_mul_f32_e32 v52, 0xbfb8aa3b, v169
	v_mul_f32_e32 v53, v38, v52
	v_mul_f32_e32 v54, v34, v52
	v_exp_f32_e32 v53, v53
	v_exp_f32_e32 v54, v54
	v_mul_f32_e32 v55, v39, v52
	v_mul_f32_e32 v56, v35, v52
	v_mul_f32_e32 v57, v40, v52
	v_mul_f32_e32 v58, v36, v52
	v_exp_f32_e32 v55, v55
	v_exp_f32_e32 v56, v56
	v_exp_f32_e32 v57, v57
	v_exp_f32_e32 v58, v58
	v_mul_f32_e32 v59, v41, v52
	v_mul_f32_e32 v52, v37, v52
	v_exp_f32_e32 v59, v59
	v_exp_f32_e32 v60, v52
	v_add_f32_e32 v52, 1.0, v53
	v_add_f32_e32 v53, 1.0, v54
	v_rcp_f32_e32 v54, v53
	v_add_f32_e32 v53, 1.0, v55
	v_add_f32_e32 v55, 1.0, v56
	v_add_f32_e32 v56, 1.0, v57
	v_add_f32_e32 v57, 1.0, v58
	v_rcp_f32_e32 v52, v52
	v_rcp_f32_e32 v53, v53
	v_rcp_f32_e32 v58, v57
	v_add_f32_e32 v57, 1.0, v59
	v_add_f32_e32 v59, 1.0, v60
	v_rcp_f32_e32 v55, v55
	v_rcp_f32_e32 v59, v59
	v_rcp_f32_e32 v56, v56
	v_rcp_f32_e32 v57, v57
	v_add_u32_e32 v51, 0x90, v141
	v_mul_f32_e32 v50, v169, v169
	v_pk_mul_f32 v[38:39], v[38:39], v[46:47]
	v_pk_mul_f32 v[46:47], v[50:51], v[52:53] op_sel_hi:[0,1]
	v_pk_mul_f32 v[38:39], v[38:39], v[46:47]
	v_pk_mul_f32 v[36:37], v[36:37], v[44:45]
	v_pk_mul_f32 v[34:35], v[34:35], v[42:43]
	v_pk_mul_f32 v[42:43], v[50:51], v[54:55] op_sel_hi:[0,1]
	v_pk_mul_f32 v[44:45], v[50:51], v[58:59] op_sel_hi:[0,1]
	v_pk_mul_f32 v[40:41], v[40:41], v[48:49]
	v_pk_mul_f32 v[48:49], v[50:51], v[56:57] op_sel_hi:[0,1]
	v_pk_mul_f32 v[44:45], v[36:37], v[44:45]
	v_pk_mul_f32 v[36:37], v[34:35], v[42:43]
	v_cvt_pk_bf16_f32 v34, v38, v39
	v_mad_i64_i32 v[38:39], s[12:13], v51, s91, v[114:115]
	v_pk_mul_f32 v[40:41], v[40:41], v[48:49]
	v_lshl_add_u64 v[38:39], v[38:39], 0, v[116:117]
	v_cvt_pk_bf16_f32 v35, v40, v41
	v_cvt_pk_bf16_f32 v36, v36, v37
	v_cvt_pk_bf16_f32 v37, v44, v45
	s_cmp_eq_u32 s98, 1
	s_cbranch_scc1 .Lwt_13
	global_store_dwordx4 v[38:39], v[34:37], off
	s_branch .Lwtd_13

.Lwtd_13:
	s_nop 1
	v_mul_f32_e32 v36, 0xbfb8aa3b, v149
	v_mul_f32_e32 v37, v22, v36
	v_mul_f32_e32 v38, v18, v36
	v_exp_f32_e32 v37, v37
	v_exp_f32_e32 v38, v38
	v_mul_f32_e32 v39, v23, v36
	v_mul_f32_e32 v40, v19, v36
	v_mul_f32_e32 v41, v24, v36
	v_mul_f32_e32 v42, v20, v36
	v_exp_f32_e32 v39, v39
	v_exp_f32_e32 v40, v40
	v_exp_f32_e32 v41, v41
	v_exp_f32_e32 v42, v42
	v_mul_f32_e32 v43, v25, v36
	v_mul_f32_e32 v36, v21, v36
	v_exp_f32_e32 v43, v43
	v_exp_f32_e32 v44, v36
	v_add_f32_e32 v36, 1.0, v37
	v_add_f32_e32 v37, 1.0, v38
	v_rcp_f32_e32 v38, v37
	v_add_f32_e32 v37, 1.0, v39
	v_add_f32_e32 v39, 1.0, v40
	v_add_f32_e32 v40, 1.0, v41
	v_add_f32_e32 v41, 1.0, v42
	v_rcp_f32_e32 v36, v36
	v_rcp_f32_e32 v37, v37
	v_rcp_f32_e32 v42, v41
	v_add_f32_e32 v41, 1.0, v43
	v_add_f32_e32 v43, 1.0, v44
	v_rcp_f32_e32 v39, v39
	v_rcp_f32_e32 v43, v43
	v_rcp_f32_e32 v40, v40
	v_rcp_f32_e32 v41, v41
	v_add_u32_e32 v35, 0xa0, v141
	v_mul_f32_e32 v34, v149, v149
	v_pk_mul_f32 v[22:23], v[22:23], v[30:31]
	v_pk_mul_f32 v[30:31], v[34:35], v[36:37] op_sel_hi:[0,1]
	v_pk_mul_f32 v[22:23], v[22:23], v[30:31]
	v_pk_mul_f32 v[20:21], v[20:21], v[28:29]
	v_pk_mul_f32 v[18:19], v[18:19], v[26:27]
	v_pk_mul_f32 v[26:27], v[34:35], v[38:39] op_sel_hi:[0,1]
	v_pk_mul_f32 v[28:29], v[34:35], v[42:43] op_sel_hi:[0,1]
	v_pk_mul_f32 v[24:25], v[24:25], v[32:33]
	v_pk_mul_f32 v[32:33], v[34:35], v[40:41] op_sel_hi:[0,1]
	v_pk_mul_f32 v[28:29], v[20:21], v[28:29]
	v_pk_mul_f32 v[20:21], v[18:19], v[26:27]
	v_cvt_pk_bf16_f32 v18, v22, v23
	v_mad_i64_i32 v[22:23], s[12:13], v35, s91, v[114:115]
	v_pk_mul_f32 v[24:25], v[24:25], v[32:33]
	v_lshl_add_u64 v[22:23], v[22:23], 0, v[116:117]
	v_cvt_pk_bf16_f32 v19, v24, v25
	v_cvt_pk_bf16_f32 v20, v20, v21
	v_cvt_pk_bf16_f32 v21, v28, v29
	s_cmp_eq_u32 s98, 1
	s_cbranch_scc1 .Lwt_14
	global_store_dwordx4 v[22:23], v[18:21], off
	s_branch .Lwtd_14

.Lwtd_14:
	s_nop 1
	v_mul_f32_e32 v20, 0xbfb8aa3b, v140
	v_mul_f32_e32 v21, v6, v20
	v_mul_f32_e32 v22, v2, v20
	v_exp_f32_e32 v21, v21
	v_exp_f32_e32 v22, v22
	v_mul_f32_e32 v23, v7, v20
	v_mul_f32_e32 v24, v3, v20
	v_mul_f32_e32 v25, v8, v20
	v_mul_f32_e32 v26, v4, v20
	v_exp_f32_e32 v23, v23
	v_exp_f32_e32 v24, v24
	v_exp_f32_e32 v25, v25
	v_exp_f32_e32 v26, v26
	v_mul_f32_e32 v27, v9, v20
	v_mul_f32_e32 v20, v5, v20
	v_exp_f32_e32 v27, v27
	v_exp_f32_e32 v28, v20
	v_add_f32_e32 v20, 1.0, v21
	v_add_f32_e32 v21, 1.0, v22
	v_rcp_f32_e32 v22, v21
	v_add_f32_e32 v21, 1.0, v23
	v_add_f32_e32 v23, 1.0, v24
	v_add_f32_e32 v24, 1.0, v25
	v_add_f32_e32 v25, 1.0, v26
	v_rcp_f32_e32 v20, v20
	v_rcp_f32_e32 v21, v21
	v_rcp_f32_e32 v26, v25
	v_add_f32_e32 v25, 1.0, v27
	v_add_f32_e32 v27, 1.0, v28
	v_rcp_f32_e32 v23, v23
	v_rcp_f32_e32 v27, v27
	v_add_u32_e32 v19, 0xb0, v141
	v_mul_f32_e32 v18, v140, v140
	v_rcp_f32_e32 v24, v24
	v_rcp_f32_e32 v25, v25
	v_pk_mul_f32 v[6:7], v[6:7], v[14:15]
	v_pk_mul_f32 v[14:15], v[18:19], v[20:21] op_sel_hi:[0,1]
	v_pk_mul_f32 v[6:7], v[6:7], v[14:15]
	v_pk_mul_f32 v[4:5], v[4:5], v[12:13]
	v_pk_mul_f32 v[2:3], v[2:3], v[10:11]
	v_pk_mul_f32 v[10:11], v[18:19], v[22:23] op_sel_hi:[0,1]
	v_pk_mul_f32 v[12:13], v[18:19], v[26:27] op_sel_hi:[0,1]
	v_pk_mul_f32 v[12:13], v[4:5], v[12:13]
	v_pk_mul_f32 v[4:5], v[2:3], v[10:11]
	v_cvt_pk_bf16_f32 v2, v6, v7
	v_mad_i64_i32 v[6:7], s[12:13], v19, s91, v[114:115]
	v_pk_mul_f32 v[8:9], v[8:9], v[16:17]
	v_pk_mul_f32 v[16:17], v[18:19], v[24:25] op_sel_hi:[0,1]
	v_lshl_add_u64 v[6:7], v[6:7], 0, v[116:117]
	v_pk_mul_f32 v[8:9], v[8:9], v[16:17]
	s_nop 0
	v_cvt_pk_bf16_f32 v3, v8, v9
	v_cvt_pk_bf16_f32 v4, v4, v5
	v_cvt_pk_bf16_f32 v5, v12, v13
	s_cmp_eq_u32 s98, 1
	s_cbranch_scc1 .Lwt_15
	global_store_dwordx4 v[6:7], v[2:5], off
	s_branch .Lwtd_15

.Lwtd_15:
	s_cbranch_vccnz .LBB0_1728
	s_andn2_b64 vcc, exec, s[28:29]
	s_cbranch_vccnz .LBB0_1711
	s_barrier
	s_branch .LBB0_1711
